# running-max update decided per row (per lane) instead of the wave-wide ballot (no VALU->SALU->VALU round trip), diff near/far + band; on top of unrolled loop
# speedup vs baseline: 1.0214x; 1.0068x over previous
; #define LAS __attribute__((address_space(3)))
; #define MFMA(a, b, c) __builtin_amdgcn_mfma_f32_32x32x16_bf16((a), (b), (c), 0, 0, 0)
; template <int DVT>
; DI void attn_step(lptr sKw, int kpitch, lptr sV, int vpitch, const bf16x8 (&qf)[4], float& m, float& l, f32x16 (&O)[DVT],
;                   const LAS float* tb, bool far, float cfar, int lane) {
;     ...
;     for (int s = 0; s < 4; ++s) {
;         kf[2 * s] = *(const LAS bf16x8*)(sKw + r * kpitch + (16 * s + 8 * h) * 2);
;         kf[2 * s + 1] = *(const LAS bf16x8*)(sKw + (32 + r) * kpitch + (16 * s + 8 * h) * 2);
;     }
;     __builtin_amdgcn_sched_barrier(0);
; #pragma unroll
;     for (int s = 0; s < 4; ++s) { p0 = MFMA(kf[2 * s], qf[s], p0); p1 = MFMA(kf[2 * s + 1], qf[s], p1); }
.Lb3_noovr:
	s_add_i32 s0, s64, 63
	s_add_i32 s65, s65, 1
	v_cmp_le_u32_e32 vcc, s64, v126
	v_cmp_ge_u32_e64 s[0:1], s0, v128
	s_and_b32 s70, s65, 1
	s_and_b32 s70, s70, s101
	s_and_b64 s[72:73], vcc, s[0:1]
	s_waitcnt lgkmcnt(0)
	s_barrier
	s_and_saveexec_b64 s[0:1], s[72:73]
	s_cbranch_execz .LBB0_220
	s_mul_i32 s71, s70, 0x4800
	v_add_u32_e32 v98, s71, v125
	v_add3_u32 v38, v98, v127, v112
	v_add3_u32 v39, v98, v129, v112
	ds_read_b128 v[34:37], v38
	ds_read_b128 v[50:53], v38 offset:32
	ds_read_b128 v[54:57], v39
	ds_read_b128 v[136:139], v39 offset:32
	ds_read_b128 v[58:61], v38 offset:64
	ds_read_b128 v[62:65], v38 offset:96
	ds_read_b128 v[140:143], v39 offset:64
	ds_read_b128 v[144:147], v39 offset:96
	s_waitcnt lgkmcnt(0)
	v_mfma_f32_32x32x16_bf16 v[34:49], v[34:37], v[66:69], 0
	v_mfma_f32_32x32x16_bf16 v[34:49], v[50:53], v[70:73], v[34:49]
	v_add_u32_e32 v50, v98, v131
	v_add_u32_e32 v135, v50, v132
	ds_read_b64_tr_b16 v[102:103], v135 offset:9216
	ds_read_b64_tr_b16 v[104:105], v135 offset:10368
	ds_read_b64_tr_b16 v[100:101], v135 offset:10432
	ds_read_b64_tr_b16 v[98:99], v135 offset:9280
	v_mfma_f32_32x32x16_bf16 v[34:49], v[58:61], v[74:77], v[34:49]
	v_mfma_f32_32x32x16_bf16 v[34:49], v[62:65], v[78:81], v[34:49]
	v_mfma_f32_32x32x16_bf16 v[50:65], v[54:57], v[66:69], 0
	v_mfma_f32_32x32x16_bf16 v[50:65], v[136:139], v[70:73], v[50:65]
	ds_read2_b32 v[136:137], v134 offset0:58 offset1:59
	ds_read2_b32 v[138:139], v134 offset0:56 offset1:57
	ds_read2_b32 v[148:149], v134 offset0:50 offset1:51
	ds_read2_b32 v[150:151], v134 offset0:48 offset1:49
	ds_read2_b32 v[152:153], v134 offset0:26 offset1:27
	ds_read2_b32 v[154:155], v134 offset0:24 offset1:25
	ds_read2_b32 v[156:157], v134 offset0:18 offset1:19
	ds_read2_b32 v[158:159], v134 offset0:16 offset1:17
	v_mfma_f32_32x32x16_bf16 v[50:65], v[140:143], v[74:77], v[50:65]
	ds_read2_b32 v[140:141], v134 offset0:42 offset1:43
	ds_read2_b32 v[142:143], v134 offset0:40 offset1:41
	ds_read2_b32 v[160:161], v134 offset0:34 offset1:35
	ds_read2_b32 v[162:163], v134 offset0:32 offset1:33
	ds_read2_b32 v[164:165], v134 offset0:10 offset1:11
	ds_read2_b32 v[166:167], v134 offset0:8 offset1:9
	ds_read2_b32 v[168:169], v134 offset0:2 offset1:3
	ds_read2_b32 v[170:171], v134 offset1:1
	v_mfma_f32_32x32x16_bf16 v[50:65], v[144:147], v[78:81], v[50:65]
	s_nop 7
	s_nop 7
	s_nop 3
	s_waitcnt lgkmcnt(0)
	v_fma_f32 v137, v34, v178, v137
	v_fma_f32 v50, v50, v178, v153
	v_fma_f32 v35, v35, v178, v136
	v_fma_f32 v51, v51, v178, v152
	v_fma_f32 v36, v36, v178, v139
	v_fma_f32 v52, v52, v178, v155
	v_fma_f32 v37, v37, v178, v138
	v_fma_f32 v53, v53, v178, v154
	s_nop 0
	v_max3_f32 v34, v137, v35, v50
	v_fma_f32 v38, v38, v178, v149
	v_fma_f32 v39, v39, v178, v148
	v_fma_f32 v40, v40, v178, v151
	v_max3_f32 v136, v36, v37, v51
	v_fma_f32 v41, v41, v178, v150
	s_nop 0
	v_max3_f32 v34, v34, v52, v53
	v_fma_f32 v54, v54, v178, v157
	v_fma_f32 v55, v55, v178, v156
	v_fma_f32 v56, v56, v178, v159
	v_fma_f32 v57, v57, v178, v158
	v_max3_f32 v136, v136, v40, v41
	s_nop 0
	v_max3_f32 v34, v34, v38, v39
	v_fma_f32 v42, v42, v178, v141
	v_fma_f32 v43, v43, v178, v140
	v_fma_f32 v44, v44, v178, v143
	v_fma_f32 v45, v45, v178, v142
	v_max3_f32 v136, v136, v56, v57
	s_nop 0
	v_max3_f32 v34, v34, v54, v55
	v_fma_f32 v58, v58, v178, v165
	v_fma_f32 v59, v59, v178, v164
	v_fma_f32 v60, v60, v178, v167
	v_fma_f32 v61, v61, v178, v166
	v_max3_f32 v136, v136, v44, v45
	s_nop 0
	v_max3_f32 v34, v34, v42, v43
	v_fma_f32 v46, v46, v178, v161
	v_fma_f32 v47, v47, v178, v160
	v_fma_f32 v48, v48, v178, v163
	v_fma_f32 v49, v49, v178, v162
	v_max3_f32 v136, v136, v60, v61
	s_nop 0
	v_max3_f32 v34, v34, v58, v59
	v_fma_f32 v62, v62, v178, v169
	v_fma_f32 v63, v63, v178, v168
	v_fma_f32 v64, v64, v178, v171
	v_fma_f32 v65, v65, v178, v170
	v_max3_f32 v136, v136, v48, v49
	s_nop 0
	v_max3_f32 v34, v34, v46, v47
	s_nop 0
	v_max3_f32 v34, v34, v62, v63
	v_max3_f32 v136, v136, v64, v65
	s_nop 0
	v_max_f32_e32 v136, v136, v136
	v_max_f32_e32 v34, v34, v34
	v_max_f32_e32 v34, v34, v136
	v_mov_b32_e32 v136, v34
	s_nop 1
	v_permlane32_swap_b32_e32 v34, v136
	v_max_f32_e32 v136, v136, v136
	v_max_f32_e32 v34, v34, v34
	v_max_f32_e32 v34, v34, v136
	v_sub_f32_e32 v136, v34, v133
	v_cmp_lt_f32_e32 vcc, s45, v136
	v_max_f32_e32 v34, v133, v34
	s_nop 0
	v_cndmask_b32_e32 v34, v133, v34, vcc
	v_sub_f32 v136, v137, v34
	v_sub_f32 v50, v50, v34
	v_sub_f32 v51, v51, v34
	v_sub_f32 v36, v36, v34
	v_sub_f32 v52, v52, v34
	v_sub_f32 v53, v53, v34
	v_sub_f32 v54, v54, v34
	v_sub_f32 v39, v39, v34
	v_sub_f32 v55, v55, v34
	v_sub_f32 v40, v40, v34
	v_sub_f32 v56, v56, v34
	v_sub_f32 v57, v57, v34
	v_sub_f32 v58, v58, v34
	v_sub_f32 v43, v43, v34
	v_sub_f32 v44, v44, v34
	v_sub_f32 v47, v47, v34
	v_sub_f32 v48, v48, v34
	v_sub_f32 v137, v35, v34
	v_sub_f32 v138, v37, v34
	v_sub_f32 v139, v38, v34
	v_sub_f32 v140, v41, v34
	v_sub_f32 v141, v42, v34
	v_sub_f32 v142, v59, v34
	v_sub_f32 v143, v60, v34
	v_sub_f32 v144, v45, v34
	v_sub_f32 v145, v61, v34
	v_sub_f32 v146, v46, v34
	v_sub_f32 v147, v62, v34
	v_sub_f32 v148, v63, v34
	v_sub_f32 v149, v64, v34
	v_sub_f32 v150, v49, v34
	v_sub_f32 v151, v65, v34
	s_nop 0
	v_exp_f32_e32 v59, v136
	v_exp_f32_e32 v35, v50
	v_exp_f32_e32 v60, v137
	v_exp_f32_e32 v37, v51
	v_exp_f32_e32 v61, v36
	v_exp_f32_e32 v38, v52
	v_exp_f32_e32 v62, v138
	v_exp_f32_e32 v41, v53
	v_exp_f32_e32 v63, v139
	v_exp_f32_e32 v42, v54
	v_exp_f32_e32 v64, v39
	v_exp_f32_e32 v45, v55
	v_exp_f32_e32 v65, v40
	v_exp_f32_e32 v46, v56
	v_exp_f32_e32 v136, v140
	v_exp_f32_e32 v49, v57
	v_exp_f32_e32 v51, v141
	v_exp_f32_e32 v36, v58
	v_exp_f32_e32 v52, v43
	v_exp_f32_e32 v39, v142
	v_exp_f32_e32 v53, v44
	v_exp_f32_e32 v40, v143
	v_exp_f32_e32 v54, v144
	v_exp_f32_e32 v43, v145
	v_exp_f32_e32 v55, v146
	v_exp_f32_e32 v44, v147
	v_exp_f32_e32 v56, v47
	v_exp_f32_e32 v47, v148
	v_exp_f32_e32 v57, v48
	v_exp_f32_e32 v48, v149
	v_exp_f32_e32 v58, v150
	v_exp_f32_e32 v50, v151
	v_add_f32 v137, v59, v35
	v_add_f32 v138, v51, v36
	v_add_f32 v139, v52, v39
	v_add_f32 v140, v53, v40
	v_add_f32 v141, v54, v43
	v_add_f32 v142, v55, v44
	s_nop 1
	s_nop 0
	v_add_f32 v137, v137, v138
	v_add_f32 v138, v60, v37
	v_add_f32 v143, v56, v47
	v_add_f32 v144, v57, v48
	v_cmp_neq_f32_e32 vcc, v34, v133
	v_add_f32 v138, v138, v139
	v_add_f32 v139, v61, v38
	v_add_f32 v145, v58, v50
	s_nop 0
	v_add_f32 v139, v139, v140
	v_add_f32 v140, v62, v41
	v_add_f32 v137, v137, v138
	s_nop 0
	v_add_f32 v140, v140, v141
	v_add_f32 v141, v63, v42
	s_nop 0
	v_add_f32 v141, v141, v142
	v_add_f32 v142, v64, v45
	v_add_f32 v138, v139, v140
	s_nop 0
	v_add_f32 v142, v142, v143
	v_add_f32 v143, v65, v46
	v_add_f32 v137, v137, v138
	s_nop 0
	v_add_f32 v143, v143, v144
	v_add_f32 v144, v136, v49
	v_add_f32 v138, v141, v142
	s_nop 0
	v_add_f32 v144, v144, v145
	s_nop 0
	v_add_f32 v139, v143, v144
	s_nop 0
	v_add_f32 v138, v138, v139
	s_nop 0
	v_add_f32 v137, v137, v138
	s_cbranch_vccz .LBB0_219
	v_sub_f32_e32 v133, v133, v34
	v_exp_f32_e32 v138, v133
	s_nop 0
	v_mul_f32_e32 v124, v124, v138
	v_pk_mul_f32 v[32:33], v[32:33], v[138:139] op_sel_hi:[1,0]
	v_pk_mul_f32 v[30:31], v[30:31], v[138:139] op_sel_hi:[1,0]
	v_pk_mul_f32 v[28:29], v[28:29], v[138:139] op_sel_hi:[1,0]
	v_pk_mul_f32 v[26:27], v[26:27], v[138:139] op_sel_hi:[1,0]
	v_pk_mul_f32 v[24:25], v[24:25], v[138:139] op_sel_hi:[1,0]
	v_pk_mul_f32 v[22:23], v[22:23], v[138:139] op_sel_hi:[1,0]
	v_pk_mul_f32 v[20:21], v[20:21], v[138:139] op_sel_hi:[1,0]
	v_pk_mul_f32 v[18:19], v[18:19], v[138:139] op_sel_hi:[1,0]
	v_pk_mul_f32 v[16:17], v[16:17], v[138:139] op_sel_hi:[1,0]
	v_pk_mul_f32 v[14:15], v[14:15], v[138:139] op_sel_hi:[1,0]
	v_pk_mul_f32 v[12:13], v[12:13], v[138:139] op_sel_hi:[1,0]
	v_pk_mul_f32 v[10:11], v[10:11], v[138:139] op_sel_hi:[1,0]
	v_pk_mul_f32 v[8:9], v[8:9], v[138:139] op_sel_hi:[1,0]
	v_pk_mul_f32 v[6:7], v[6:7], v[138:139] op_sel_hi:[1,0]
	v_pk_mul_f32 v[4:5], v[4:5], v[138:139] op_sel_hi:[1,0]
	v_pk_mul_f32 v[2:3], v[2:3], v[138:139] op_sel_hi:[1,0]

; #define LAS __attribute__((address_space(3)))
; #define MFMA(a, b, c) __builtin_amdgcn_mfma_f32_32x32x16_bf16((a), (b), (c), 0, 0, 0)
; template <typename F>
; DI void diff_step(lptr sK, lptr sV, int kx0, int vl0, const bf16x8 (&qf)[4], float& m, float& l, f32x16 (&O)[4],
;                   const LAS float* tb, bool far, float cfar, int lane, F&& mid) {
;     ...
;     lptr kr = sK + r * 256;
;     bf16x8 kf[8];
; #pragma unroll
;     for (int s = 0; s < 4; ++s) {
;         const int co = (kx0 ^ (2 * s)) * 16;
;         kf[2 * s] = *(const LAS bf16x8*)(kr + co);
;         kf[2 * s + 1] = *(const LAS bf16x8*)(kr + 8192 + co);
;     }
;     __builtin_amdgcn_sched_barrier(0);
;     mid();
;     __builtin_amdgcn_sched_barrier(0);
; #pragma unroll
;     for (int s = 0; s < 4; ++s) { p0 = MFMA(kf[2 * s], qf[s], p0); p1 = MFMA(kf[2 * s + 1], qf[s], p1); }
.Ldu_A:
	s_waitcnt vmcnt(0)
	s_waitcnt lgkmcnt(0)
	s_barrier
	ds_read_b128 v[80:83], v14
	ds_read_b128 v[84:87], v14 offset:8192
	ds_read_b128 v[120:123], v15
	ds_read_b128 v[6:9], v15 offset:8192
	ds_read_b128 v[116:119], v221
	ds_read_b128 v[2:5], v221 offset:8192
	ds_read_b128 v[10:13], v222
	ds_read_b128 v[112:115], v222 offset:8192
	v_add_u32_e32 v220, 1, v220
	s_add_u32 s72, s63, 0x8000
	s_mov_b32 m0, s72
	s_nop 0
	global_load_lds_dwordx4 v170, s[64:65]
	s_add_u32 s72, s63, 0xc000
	s_mov_b32 m0, s72
	s_nop 0
	global_load_lds_dwordx4 v170, s[70:71]
	s_add_u32 s72, s63, 0x8400
	s_mov_b32 m0, s72
	s_nop 0
	global_load_lds_dwordx4 v172, s[64:65]
	s_add_u32 s72, s63, 0xc400
	s_mov_b32 m0, s72
	s_nop 0
	global_load_lds_dwordx4 v172, s[70:71]
	s_add_u32 s64, s64, 0xe0000
	s_addc_u32 s65, s65, 0
	s_add_u32 s70, s70, 0xe0000
	s_addc_u32 s71, s71, 0
	v_cmp_gt_i32_e32 vcc, s42, v217
	s_waitcnt lgkmcnt(7)
	v_mfma_f32_32x32x16_bf16 v[96:111], v[80:83], v[144:147], 0
	s_waitcnt lgkmcnt(6)
	v_mfma_f32_32x32x16_bf16 v[80:95], v[84:87], v[144:147], 0
	s_waitcnt lgkmcnt(5)
	v_mfma_f32_32x32x16_bf16 v[96:111], v[120:123], v[148:151], v[96:111]
	s_waitcnt lgkmcnt(4)
	v_mfma_f32_32x32x16_bf16 v[80:95], v[6:9], v[148:151], v[80:95]
	s_waitcnt lgkmcnt(3)
	v_mfma_f32_32x32x16_bf16 v[96:111], v[116:119], v[152:155], v[96:111]
	s_waitcnt lgkmcnt(2)
	v_mfma_f32_32x32x16_bf16 v[80:95], v[2:5], v[152:155], v[80:95]
	ds_read_b64_tr_b16 v[2:3], v199 offset:16384
	ds_read_b64_tr_b16 v[4:5], v210 offset:18432
	ds_read_b64_tr_b16 v[6:7], v211 offset:16384
	ds_read_b64_tr_b16 v[8:9], v212 offset:18432
	s_waitcnt lgkmcnt(5)
	v_mfma_f32_32x32x16_bf16 v[96:111], v[10:13], v[156:159], v[96:111]
	ds_read_b64_tr_b16 v[10:11], v213 offset:16384
	ds_read_b64_tr_b16 v[12:13], v214 offset:18432
	ds_read_b64_tr_b16 v[160:161], v215 offset:16384
	ds_read_b64_tr_b16 v[162:163], v216 offset:18432
	s_waitcnt lgkmcnt(8)
	v_mfma_f32_32x32x16_bf16 v[80:95], v[112:115], v[156:159], v[80:95]
	v_max_f32_e32 v228, v226, v226
	s_and_saveexec_b64 s[22:23], vcc
	s_xor_b64 s[22:23], exec, s[22:23]
	s_cbranch_execz .LBB0_258_a
	ds_read2_b32 v[112:113], v218 offset0:58 offset1:59
	ds_read2_b32 v[114:115], v218 offset0:56 offset1:57
	ds_read2_b32 v[116:117], v218 offset0:50 offset1:51
	ds_read2_b32 v[118:119], v218 offset0:48 offset1:49
	ds_read2_b32 v[120:121], v218 offset0:26 offset1:27
	ds_read2_b32 v[122:123], v218 offset0:24 offset1:25
	ds_read2_b32 v[124:125], v218 offset0:18 offset1:19
	ds_read2_b32 v[126:127], v218 offset0:16 offset1:17
	ds_read2_b32 v[128:129], v218 offset0:42 offset1:43
	ds_read2_b32 v[130:131], v218 offset0:40 offset1:41
	ds_read2_b32 v[132:133], v218 offset0:34 offset1:35
	ds_read2_b32 v[134:135], v218 offset0:32 offset1:33
	ds_read2_b32 v[136:137], v218 offset0:10 offset1:11
	ds_read2_b32 v[138:139], v218 offset0:8 offset1:9
	ds_read2_b32 v[140:141], v218 offset0:2 offset1:3
	ds_read2_b32 v[142:143], v218 offset1:1
	s_nop 7
	s_nop 7
	s_nop 3
	s_waitcnt lgkmcnt(14)
	v_fma_f32 v96, v96, v178, v113
	s_waitcnt lgkmcnt(11)
	v_fma_f32 v80, v80, v178, v121
	v_fma_f32 v97, v97, v178, v112
	v_fma_f32 v81, v81, v178, v120
	v_fma_f32 v98, v98, v178, v115
	s_waitcnt lgkmcnt(10)
	v_fma_f32 v82, v82, v178, v123
	v_fma_f32 v99, v99, v178, v114
	v_fma_f32 v83, v83, v178, v122
	v_max3_f32 v112, v96, v97, v80
	v_fma_f32 v100, v100, v178, v117
	v_fma_f32 v101, v101, v178, v116
	v_fma_f32 v102, v102, v178, v119
	s_nop 0
	v_max3_f32 v113, v98, v99, v81
	v_fma_f32 v103, v103, v178, v118
	v_max3_f32 v112, v112, v82, v83
	s_waitcnt lgkmcnt(9)
	v_fma_f32 v84, v84, v178, v125
	v_fma_f32 v85, v85, v178, v124
	s_waitcnt lgkmcnt(8)
	v_fma_f32 v86, v86, v178, v127
	v_fma_f32 v87, v87, v178, v126
	v_max3_f32 v113, v113, v102, v103
	v_max3_f32 v112, v112, v100, v101
	s_waitcnt lgkmcnt(7)
	v_fma_f32 v104, v104, v178, v129
	v_fma_f32 v105, v105, v178, v128
	s_waitcnt lgkmcnt(6)
	v_fma_f32 v106, v106, v178, v131
	v_fma_f32 v107, v107, v178, v130
	v_max3_f32 v113, v113, v86, v87
	v_max3_f32 v112, v112, v84, v85
	s_waitcnt lgkmcnt(3)
	v_fma_f32 v88, v88, v178, v137
	v_fma_f32 v89, v89, v178, v136
	s_waitcnt lgkmcnt(2)
	v_fma_f32 v90, v90, v178, v139
	v_fma_f32 v91, v91, v178, v138
	v_max3_f32 v113, v113, v106, v107
	v_max3_f32 v112, v112, v104, v105
	v_fma_f32 v108, v108, v178, v133
	v_fma_f32 v109, v109, v178, v132
	v_fma_f32 v110, v110, v178, v135
	v_fma_f32 v111, v111, v178, v134
	s_nop 0
	v_max3_f32 v113, v113, v90, v91
	v_max3_f32 v112, v112, v88, v89
	s_waitcnt lgkmcnt(1)
	v_fma_f32 v92, v92, v178, v141
	v_fma_f32 v93, v93, v178, v140
	s_waitcnt lgkmcnt(0)
	v_fma_f32 v94, v94, v178, v143
	v_fma_f32 v95, v95, v178, v142
	v_max3_f32 v113, v113, v110, v111
	v_max3_f32 v112, v112, v108, v109
	s_nop 0
	v_max3_f32 v112, v112, v92, v93
	v_max3_f32 v113, v113, v94, v95
	s_nop 0
	v_max_f32_e32 v113, v113, v113
	v_max_f32_e32 v112, v112, v112
	v_max_f32_e32 v112, v112, v113
	v_mov_b32_e32 v113, v112
	s_nop 1
	v_permlane32_swap_b32_e32 v112, v113
	v_max_f32_e32 v113, v113, v113
	v_max_f32_e32 v112, v112, v112
	v_max_f32_e32 v112, v112, v113
	v_sub_f32_e32 v113, v112, v226
	v_cmp_lt_f32_e32 vcc, s45, v113
	v_max_f32_e32 v112, v226, v112
	s_nop 0
	v_cndmask_b32_e32 v227, v226, v112, vcc
	v_sub_f32 v112, v96, v227
	v_sub_f32 v128, v80, v227
	v_sub_f32 v113, v97, v227
	v_sub_f32 v129, v81, v227
	v_sub_f32 v114, v98, v227
	v_sub_f32 v130, v82, v227
	v_sub_f32 v115, v99, v227
	v_sub_f32 v131, v83, v227
	v_sub_f32 v116, v100, v227
	v_sub_f32 v132, v84, v227
	v_sub_f32 v117, v101, v227
	v_sub_f32 v133, v85, v227
	v_sub_f32 v118, v102, v227
	v_sub_f32 v134, v86, v227
	v_sub_f32 v119, v103, v227
	v_sub_f32 v135, v87, v227
	v_sub_f32 v120, v104, v227
	v_sub_f32 v136, v88, v227
	v_sub_f32 v121, v105, v227
	v_sub_f32 v137, v89, v227
	v_sub_f32 v122, v106, v227
	v_sub_f32 v138, v90, v227
	v_sub_f32 v123, v107, v227
	v_sub_f32 v139, v91, v227
	v_sub_f32 v124, v108, v227
	v_sub_f32 v140, v92, v227
	v_sub_f32 v125, v109, v227
	v_sub_f32 v141, v93, v227
	v_sub_f32 v126, v110, v227
	v_sub_f32 v142, v94, v227
	v_sub_f32 v127, v111, v227
	v_sub_f32 v143, v95, v227
.LBB0_258_a:
	s_andn2_saveexec_b64 s[22:23], s[22:23]
	s_cbranch_execz .LBB0_260_a
	s_nop 7
	s_nop 7
	s_nop 3
	v_sub_f32_e32 v243, v198, v226
	v_max3_f32 v244, v96, v97, v80
	v_fma_f32 v112, v96, v178, v243
	v_fma_f32 v128, v80, v178, v243
	v_max3_f32 v245, v98, v99, v81
	v_fma_f32 v113, v97, v178, v243
	v_fma_f32 v129, v81, v178, v243
	v_max3_f32 v244, v244, v82, v83
	v_fma_f32 v114, v98, v178, v243
	v_fma_f32 v130, v82, v178, v243
	v_max3_f32 v245, v245, v102, v103
	v_fma_f32 v115, v99, v178, v243
	v_fma_f32 v131, v83, v178, v243
	v_max3_f32 v244, v244, v100, v101
	v_fma_f32 v116, v100, v178, v243
	v_fma_f32 v132, v84, v178, v243
	v_max3_f32 v245, v245, v86, v87
	v_fma_f32 v117, v101, v178, v243
	v_fma_f32 v133, v85, v178, v243
	v_max3_f32 v244, v244, v84, v85
	v_fma_f32 v118, v102, v178, v243
	v_fma_f32 v134, v86, v178, v243
	v_max3_f32 v245, v245, v106, v107
	v_fma_f32 v119, v103, v178, v243
	v_fma_f32 v135, v87, v178, v243
	v_max3_f32 v244, v244, v104, v105
	v_fma_f32 v120, v104, v178, v243
	v_fma_f32 v136, v88, v178, v243
	v_max3_f32 v245, v245, v90, v91
	v_fma_f32 v121, v105, v178, v243
	v_fma_f32 v137, v89, v178, v243
	v_max3_f32 v244, v244, v88, v89
	v_fma_f32 v122, v106, v178, v243
	v_fma_f32 v138, v90, v178, v243
	v_max3_f32 v245, v245, v110, v111
	v_fma_f32 v123, v107, v178, v243
	v_fma_f32 v139, v91, v178, v243
	v_max3_f32 v244, v244, v108, v109
	v_fma_f32 v124, v108, v178, v243
	v_fma_f32 v140, v92, v178, v243
	v_max3_f32 v245, v245, v94, v95
	v_fma_f32 v125, v109, v178, v243
	v_fma_f32 v141, v93, v178, v243
	v_max3_f32 v244, v244, v92, v93
	v_fma_f32 v126, v110, v178, v243
	v_fma_f32 v142, v94, v178, v243
	v_fma_f32 v127, v111, v178, v243
	v_fma_f32 v143, v95, v178, v243
	v_max_f32_e32 v244, v244, v245
	v_mov_b32_e32 v245, v244
	s_nop 1
	v_permlane32_swap_b32_e32 v244, v245
	v_max_f32_e32 v244, v244, v245
	v_fmamk_f32 v244, v244, 0x3e38aa3b, v198
	v_sub_f32_e32 v245, v244, v226
	v_cmp_lt_f32_e32 vcc, s45, v245
	v_max_f32_e32 v244, v226, v244
	s_nop 0
	v_cndmask_b32_e32 v227, v226, v244, vcc
	s_nop 2
	s_cbranch_vccz .Ldf_far_nofix_a
	v_sub_f32_e32 v243, v198, v227
	v_fma_f32 v112, v96, v178, v243
	v_fma_f32 v128, v80, v178, v243
	v_fma_f32 v113, v97, v178, v243
	v_fma_f32 v129, v81, v178, v243
	v_fma_f32 v114, v98, v178, v243
	v_fma_f32 v130, v82, v178, v243
	v_fma_f32 v115, v99, v178, v243
	v_fma_f32 v131, v83, v178, v243
	v_fma_f32 v116, v100, v178, v243
	v_fma_f32 v132, v84, v178, v243
	v_fma_f32 v117, v101, v178, v243
	v_fma_f32 v133, v85, v178, v243
	v_fma_f32 v118, v102, v178, v243
	v_fma_f32 v134, v86, v178, v243
	v_fma_f32 v119, v103, v178, v243
	v_fma_f32 v135, v87, v178, v243
	v_fma_f32 v120, v104, v178, v243
	v_fma_f32 v136, v88, v178, v243
	v_fma_f32 v121, v105, v178, v243
	v_fma_f32 v137, v89, v178, v243
	v_fma_f32 v122, v106, v178, v243
	v_fma_f32 v138, v90, v178, v243
	v_fma_f32 v123, v107, v178, v243
	v_fma_f32 v139, v91, v178, v243
	v_fma_f32 v124, v108, v178, v243
	v_fma_f32 v140, v92, v178, v243
	v_fma_f32 v125, v109, v178, v243
	v_fma_f32 v141, v93, v178, v243
	v_fma_f32 v126, v110, v178, v243
	v_fma_f32 v142, v94, v178, v243
	v_fma_f32 v127, v111, v178, v243
	v_fma_f32 v143, v95, v178, v243

; #define MFMA(a, b, c) __builtin_amdgcn_mfma_f32_32x32x16_bf16((a), (b), (c), 0, 0, 0)
; template <typename F>
; DI void diff_step(lptr sK, lptr sV, int kx0, int vl0, const bf16x8 (&qf)[4], float& m, float& l, f32x16 (&O)[4],
;                   const LAS float* tb, bool far, float cfar, int lane, F&& mid) {
;     ...
;     mid();
;     __builtin_amdgcn_sched_barrier(0);
; #pragma unroll
;     for (int s = 0; s < 4; ++s) { p0 = MFMA(kf[2 * s], qf[s], p0); p1 = MFMA(kf[2 * s + 1], qf[s], p1); }
;     ...
;     ATTN_TAIL(4, VADDR_SWZ)
.LBB0_256_b:
	s_or_b64 exec, exec, s[22:23]
	v_cmp_gt_i32_e32 vcc, s42, v217
	s_waitcnt lgkmcnt(7)
	v_mfma_f32_32x32x16_bf16 v[96:111], v[80:83], v[144:147], 0
	s_waitcnt lgkmcnt(6)
	v_mfma_f32_32x32x16_bf16 v[80:95], v[84:87], v[144:147], 0
	s_waitcnt lgkmcnt(5)
	v_mfma_f32_32x32x16_bf16 v[96:111], v[120:123], v[148:151], v[96:111]
	s_waitcnt lgkmcnt(4)
	v_mfma_f32_32x32x16_bf16 v[80:95], v[6:9], v[148:151], v[80:95]
	s_waitcnt lgkmcnt(3)
	v_mfma_f32_32x32x16_bf16 v[96:111], v[116:119], v[152:155], v[96:111]
	s_waitcnt lgkmcnt(2)
	v_mfma_f32_32x32x16_bf16 v[80:95], v[2:5], v[152:155], v[80:95]
	ds_read_b64_tr_b16 v[2:3], v199 offset:49152
	ds_read_b64_tr_b16 v[4:5], v210 offset:51200
	ds_read_b64_tr_b16 v[6:7], v211 offset:49152
	ds_read_b64_tr_b16 v[8:9], v212 offset:51200
	s_waitcnt lgkmcnt(5)
	v_mfma_f32_32x32x16_bf16 v[96:111], v[10:13], v[156:159], v[96:111]
	ds_read_b64_tr_b16 v[10:11], v213 offset:49152
	ds_read_b64_tr_b16 v[12:13], v214 offset:51200
	ds_read_b64_tr_b16 v[160:161], v215 offset:49152
	ds_read_b64_tr_b16 v[162:163], v216 offset:51200
	s_waitcnt lgkmcnt(8)
	v_mfma_f32_32x32x16_bf16 v[80:95], v[112:115], v[156:159], v[80:95]
	v_max_f32_e32 v228, v226, v226
	s_and_saveexec_b64 s[22:23], vcc
	s_xor_b64 s[22:23], exec, s[22:23]
	s_cbranch_execz .LBB0_258_b
	ds_read2_b32 v[112:113], v218 offset0:58 offset1:59
	ds_read2_b32 v[114:115], v218 offset0:56 offset1:57
	ds_read2_b32 v[116:117], v218 offset0:50 offset1:51
	ds_read2_b32 v[118:119], v218 offset0:48 offset1:49
	ds_read2_b32 v[120:121], v218 offset0:26 offset1:27
	ds_read2_b32 v[122:123], v218 offset0:24 offset1:25
	ds_read2_b32 v[124:125], v218 offset0:18 offset1:19
	ds_read2_b32 v[126:127], v218 offset0:16 offset1:17
	ds_read2_b32 v[128:129], v218 offset0:42 offset1:43
	ds_read2_b32 v[130:131], v218 offset0:40 offset1:41
	ds_read2_b32 v[132:133], v218 offset0:34 offset1:35
	ds_read2_b32 v[134:135], v218 offset0:32 offset1:33
	ds_read2_b32 v[136:137], v218 offset0:10 offset1:11
	ds_read2_b32 v[138:139], v218 offset0:8 offset1:9
	ds_read2_b32 v[140:141], v218 offset0:2 offset1:3
	ds_read2_b32 v[142:143], v218 offset1:1
	s_nop 7
	s_nop 7
	s_nop 3
	s_waitcnt lgkmcnt(14)
	v_fma_f32 v96, v96, v178, v113
	s_waitcnt lgkmcnt(11)
	v_fma_f32 v80, v80, v178, v121
	v_fma_f32 v97, v97, v178, v112
	v_fma_f32 v81, v81, v178, v120
	v_fma_f32 v98, v98, v178, v115
	s_waitcnt lgkmcnt(10)
	v_fma_f32 v82, v82, v178, v123
	v_fma_f32 v99, v99, v178, v114
	v_fma_f32 v83, v83, v178, v122
	v_max3_f32 v112, v96, v97, v80
	v_fma_f32 v100, v100, v178, v117
	v_fma_f32 v101, v101, v178, v116
	v_fma_f32 v102, v102, v178, v119
	s_nop 0
	v_max3_f32 v113, v98, v99, v81
	v_fma_f32 v103, v103, v178, v118
	v_max3_f32 v112, v112, v82, v83
	s_waitcnt lgkmcnt(9)
	v_fma_f32 v84, v84, v178, v125
	v_fma_f32 v85, v85, v178, v124
	s_waitcnt lgkmcnt(8)
	v_fma_f32 v86, v86, v178, v127
	v_fma_f32 v87, v87, v178, v126
	v_max3_f32 v113, v113, v102, v103
	v_max3_f32 v112, v112, v100, v101
	s_waitcnt lgkmcnt(7)
	v_fma_f32 v104, v104, v178, v129
	v_fma_f32 v105, v105, v178, v128
	s_waitcnt lgkmcnt(6)
	v_fma_f32 v106, v106, v178, v131
	v_fma_f32 v107, v107, v178, v130
	v_max3_f32 v113, v113, v86, v87
	v_max3_f32 v112, v112, v84, v85
	s_waitcnt lgkmcnt(3)
	v_fma_f32 v88, v88, v178, v137
	v_fma_f32 v89, v89, v178, v136
	s_waitcnt lgkmcnt(2)
	v_fma_f32 v90, v90, v178, v139
	v_fma_f32 v91, v91, v178, v138
	v_max3_f32 v113, v113, v106, v107
	v_max3_f32 v112, v112, v104, v105
	v_fma_f32 v108, v108, v178, v133
	v_fma_f32 v109, v109, v178, v132
	v_fma_f32 v110, v110, v178, v135
	v_fma_f32 v111, v111, v178, v134
	s_nop 0
	v_max3_f32 v113, v113, v90, v91
	v_max3_f32 v112, v112, v88, v89
	s_waitcnt lgkmcnt(1)
	v_fma_f32 v92, v92, v178, v141
	v_fma_f32 v93, v93, v178, v140
	s_waitcnt lgkmcnt(0)
	v_fma_f32 v94, v94, v178, v143
	v_fma_f32 v95, v95, v178, v142
	v_max3_f32 v113, v113, v110, v111
	v_max3_f32 v112, v112, v108, v109
	s_nop 0
	v_max3_f32 v112, v112, v92, v93
	v_max3_f32 v113, v113, v94, v95
	s_nop 0
	v_max_f32_e32 v113, v113, v113
	v_max_f32_e32 v112, v112, v112
	v_max_f32_e32 v112, v112, v113
	v_mov_b32_e32 v113, v112
	s_nop 1
	v_permlane32_swap_b32_e32 v112, v113
	v_max_f32_e32 v113, v113, v113
	v_max_f32_e32 v112, v112, v112
	v_max_f32_e32 v112, v112, v113
	v_sub_f32_e32 v113, v112, v226
	v_cmp_lt_f32_e32 vcc, s45, v113
	v_max_f32_e32 v112, v226, v112
	s_nop 0
	v_cndmask_b32_e32 v227, v226, v112, vcc
	v_sub_f32 v112, v96, v227
	v_sub_f32 v128, v80, v227
	v_sub_f32 v113, v97, v227
	v_sub_f32 v129, v81, v227
	v_sub_f32 v114, v98, v227
	v_sub_f32 v130, v82, v227
	v_sub_f32 v115, v99, v227
	v_sub_f32 v131, v83, v227
	v_sub_f32 v116, v100, v227
	v_sub_f32 v132, v84, v227
	v_sub_f32 v117, v101, v227
	v_sub_f32 v133, v85, v227
	v_sub_f32 v118, v102, v227
	v_sub_f32 v134, v86, v227
	v_sub_f32 v119, v103, v227
	v_sub_f32 v135, v87, v227
	v_sub_f32 v120, v104, v227
	v_sub_f32 v136, v88, v227
	v_sub_f32 v121, v105, v227
	v_sub_f32 v137, v89, v227
	v_sub_f32 v122, v106, v227
	v_sub_f32 v138, v90, v227
	v_sub_f32 v123, v107, v227
	v_sub_f32 v139, v91, v227
	v_sub_f32 v124, v108, v227
	v_sub_f32 v140, v92, v227
	v_sub_f32 v125, v109, v227
	v_sub_f32 v141, v93, v227
	v_sub_f32 v126, v110, v227
	v_sub_f32 v142, v94, v227
	v_sub_f32 v127, v111, v227
	v_sub_f32 v143, v95, v227
